# a29 + kernel-start XCD mask post no longer waited (fire-and-forget atomic_or; consumed only at the first grid barrier census)
# speedup vs baseline: 1.0017x; 1.0000x over previous
_Z10fwd_kernel6Params:
	s_load_dwordx8 s[20:27], s[0:1], 0x80
	s_load_dword s30, s[0:1], 0xa8
	s_load_dwordx2 s[28:29], s[0:1], 0xa0
	s_add_u32 s6, s0, 0xa0
	v_and_b32_e32 v1, 0x3ff, v0
	s_addc_u32 s7, s1, 0
	v_cmp_gt_u32_e32 vcc, 2, v1
	s_and_saveexec_b64 s[4:5], vcc
	v_lshl_add_u32 v2, v1, 2, 0
	v_add_u32_e32 v2, 0x20000, v2
	v_mov_b32_e32 v3, 0
	ds_write_b32 v2, v3
	s_or_b64 exec, exec, s[4:5]
	s_waitcnt lgkmcnt(0)
	s_add_u32 s94, s26, 0xfe00000
	s_barrier
	s_getreg_b32 s3, hwreg(HW_REG_XCC_ID, 0, 4)
	s_addc_u32 s95, s27, 0
	s_and_b32 s84, s3, 15
	v_cmp_eq_u32_e64 s[8:9], 0, v1
	s_mov_b64 s[4:5], exec
	s_nop 0
	v_writelane_b32 v248, s8, 0
	s_nop 1
	v_writelane_b32 v248, s9, 1
	s_and_b64 s[8:9], s[4:5], s[8:9]
	s_mov_b64 exec, s[8:9]
	s_cbranch_execz .LBB0_5
	s_mov_b64 s[10:11], exec
	v_mbcnt_lo_u32_b32 v2, s10, 0
	v_mbcnt_hi_u32_b32 v2, s11, v2
	v_cmp_eq_u32_e32 vcc, 0, v2
	s_and_b64 s[8:9], exec, vcc
	s_mov_b64 exec, s[8:9]
	s_cbranch_execz .LBB0_5
	s_lshl_b32 s3, s84, 8
	s_bcnt1_i32_b64 s8, s[10:11]
	v_mov_b32_e32 v2, s3
	v_mov_b32_e32 v3, s8
	s_and_b32 s12, s2, 7
	s_lshl_b32 s12, 1, s12
	v_mov_b32_e32 v5, s12
	s_lshl_b32 s13, s84, 6
	v_mov_b32_e32 v6, s13
	v_add_u32_e32 v6, 0x3800, v6
	global_atomic_or v6, v5, s[94:95]
	global_atomic_add v2, v3, s[94:95] offset:1024
